# attention band loop: per-wave skip of the causal-mask block when the tile is fully visible for the wave
# speedup vs baseline: 1.0103x; 1.0023x over previous
.LBB0_851:
	s_add_u32 s23, s64, s58
	s_addc_u32 s70, s65, s59
	s_add_u32 s6, s23, 0x10000
	s_addc_u32 s7, s70, 0
	s_add_i32 s71, s13, s95
	s_add_i32 s68, s22, s86
	s_add_i32 s69, s71, 2
	s_cmp_lt_i32 s69, 0
	s_mov_b32 m0, s68
	s_nop 0
	global_load_lds_dwordx4 v216, s[6:7]
	s_cbranch_scc1 .LBB0_853
	v_subrev_u32_e32 v85, 64, v245
	v_cmp_le_i32_e32 vcc, v85, v244
	s_cmp_eq_u64 vcc, exec
	s_cbranch_scc1 .LBB0_853
	v_cmp_le_i32_e32 vcc, v85, v14
	v_subrev_u32_e32 v86, 62, v245
	s_nop 0
	v_cndmask_b32_e32 v112, v203, v112, vcc
	v_cmp_lt_i32_e32 vcc, v85, v213
	s_nop 1
	v_cndmask_b32_e32 v129, v203, v129, vcc
	v_cmp_le_i32_e32 vcc, v85, v213
	s_nop 1
	v_cndmask_b32_e32 v128, v203, v128, vcc
	v_cmp_le_i32_e32 vcc, v85, v15
	s_nop 1
	v_cndmask_b32_e32 v113, v203, v113, vcc
	v_cmp_le_i32_e32 vcc, v86, v213
	v_subrev_u32_e32 v86, 61, v245
	s_nop 0
	v_cndmask_b32_e32 v130, v203, v130, vcc
	v_cmp_le_i32_e32 vcc, v85, v219
	s_nop 1
	v_cndmask_b32_e32 v114, v203, v114, vcc
	v_cmp_le_i32_e32 vcc, v86, v213
	s_nop 1
	v_cndmask_b32_e32 v131, v203, v131, vcc
	v_cmp_le_i32_e32 vcc, v85, v220
	s_nop 1
	v_cndmask_b32_e32 v115, v203, v115, vcc
	v_cmp_le_i32_e32 vcc, v85, v221
	s_nop 1
	v_cndmask_b32_e32 v132, v203, v132, vcc
	v_cmp_le_i32_e32 vcc, v85, v222
	s_nop 1
	v_cndmask_b32_e32 v116, v203, v116, vcc
	v_cmp_le_i32_e32 vcc, v85, v223
	s_nop 1
	v_cndmask_b32_e32 v133, v203, v133, vcc
	v_cmp_le_i32_e32 vcc, v85, v224
	s_nop 1
	v_cndmask_b32_e32 v117, v203, v117, vcc
	v_cmp_le_i32_e32 vcc, v85, v225
	s_nop 1
	v_cndmask_b32_e32 v134, v203, v134, vcc
	v_cmp_le_i32_e32 vcc, v85, v226
	s_nop 1
	v_cndmask_b32_e32 v118, v203, v118, vcc
	v_cmp_le_i32_e32 vcc, v85, v227
	s_nop 1
	v_cndmask_b32_e32 v135, v203, v135, vcc
	v_cmp_le_i32_e32 vcc, v85, v228
	s_nop 1
	v_cndmask_b32_e32 v119, v203, v119, vcc
	v_cmp_le_i32_e32 vcc, v85, v229
	s_nop 1
	v_cndmask_b32_e32 v136, v203, v136, vcc
	v_cmp_le_i32_e32 vcc, v85, v230
	s_nop 1
	v_cndmask_b32_e32 v120, v203, v120, vcc
	v_cmp_le_i32_e32 vcc, v85, v231
	s_nop 1
	v_cndmask_b32_e32 v137, v203, v137, vcc
	v_cmp_le_i32_e32 vcc, v85, v232
	s_nop 1
	v_cndmask_b32_e32 v121, v203, v121, vcc
	v_cmp_le_i32_e32 vcc, v85, v233
	s_nop 1
	v_cndmask_b32_e32 v138, v203, v138, vcc
	v_cmp_le_i32_e32 vcc, v85, v234
	s_nop 1
	v_cndmask_b32_e32 v122, v203, v122, vcc
	v_cmp_le_i32_e32 vcc, v85, v235
	s_nop 1
	v_cndmask_b32_e32 v139, v203, v139, vcc
	v_cmp_le_i32_e32 vcc, v85, v236
	s_nop 1
	v_cndmask_b32_e32 v123, v203, v123, vcc
	v_cmp_le_i32_e32 vcc, v85, v237
	s_nop 1
	v_cndmask_b32_e32 v140, v203, v140, vcc
	v_cmp_le_i32_e32 vcc, v85, v238
	s_nop 1
	v_cndmask_b32_e32 v124, v203, v124, vcc
	v_cmp_le_i32_e32 vcc, v85, v239
	s_nop 1
	v_cndmask_b32_e32 v141, v203, v141, vcc
	v_cmp_le_i32_e32 vcc, v85, v240
	s_nop 1
	v_cndmask_b32_e32 v125, v203, v125, vcc
	v_cmp_le_i32_e32 vcc, v85, v241
	s_nop 1
	v_cndmask_b32_e32 v142, v203, v142, vcc
	v_cmp_le_i32_e32 vcc, v85, v242
	s_nop 1
	v_cndmask_b32_e32 v126, v203, v126, vcc
	v_cmp_le_i32_e32 vcc, v85, v243
	s_nop 1
	v_cndmask_b32_e32 v143, v203, v143, vcc
	v_cmp_le_i32_e32 vcc, v85, v244
	s_nop 1
	v_cndmask_b32_e32 v127, v203, v127, vcc

.LBB0_862:
	s_add_i32 s71, s71, 3
	s_cmp_lt_i32 s71, 0
	s_cbranch_scc1 .LBB0_864
	v_cmp_le_i32_e32 vcc, v245, v244
	s_cmp_eq_u64 vcc, exec
	s_cbranch_scc1 .LBB0_864
	v_cmp_le_i32_e32 vcc, v245, v14
	v_add_u32_e32 v117, 2, v245
	s_nop 0
	v_cndmask_b32_e32 v80, v203, v80, vcc
	v_cmp_lt_i32_e32 vcc, v245, v213
	s_nop 1
	v_cndmask_b32_e32 v97, v203, v97, vcc
	v_cmp_le_i32_e32 vcc, v245, v213
	s_nop 1
	v_cndmask_b32_e32 v96, v203, v96, vcc
	v_cmp_le_i32_e32 vcc, v245, v15
	s_nop 1
	v_cndmask_b32_e32 v81, v203, v81, vcc
	v_cmp_le_i32_e32 vcc, v117, v213
	v_add_u32_e32 v117, 3, v245
	s_nop 0
	v_cndmask_b32_e32 v98, v203, v98, vcc
	v_cmp_le_i32_e32 vcc, v245, v219
	s_nop 1
	v_cndmask_b32_e32 v82, v203, v82, vcc
	v_cmp_le_i32_e32 vcc, v117, v213
	s_nop 1
	v_cndmask_b32_e32 v99, v203, v99, vcc
	v_cmp_le_i32_e32 vcc, v245, v220
	s_nop 1
	v_cndmask_b32_e32 v83, v203, v83, vcc
	v_cmp_le_i32_e32 vcc, v245, v221
	s_nop 1
	v_cndmask_b32_e32 v100, v203, v100, vcc
	v_cmp_le_i32_e32 vcc, v245, v222
	s_nop 1
	v_cndmask_b32_e32 v84, v203, v84, vcc
	v_cmp_le_i32_e32 vcc, v245, v223
	s_nop 1
	v_cndmask_b32_e32 v101, v203, v101, vcc
	v_cmp_le_i32_e32 vcc, v245, v224
	s_nop 1
	v_cndmask_b32_e32 v85, v203, v85, vcc
	v_cmp_le_i32_e32 vcc, v245, v225
	s_nop 1
	v_cndmask_b32_e32 v102, v203, v102, vcc
	v_cmp_le_i32_e32 vcc, v245, v226
	s_nop 1
	v_cndmask_b32_e32 v86, v203, v86, vcc
	v_cmp_le_i32_e32 vcc, v245, v227
	s_nop 1
	v_cndmask_b32_e32 v103, v203, v103, vcc
	v_cmp_le_i32_e32 vcc, v245, v228
	s_nop 1
	v_cndmask_b32_e32 v87, v203, v87, vcc
	v_cmp_le_i32_e32 vcc, v245, v229
	s_nop 1
	v_cndmask_b32_e32 v104, v203, v104, vcc
	v_cmp_le_i32_e32 vcc, v245, v230
	s_nop 1
	v_cndmask_b32_e32 v88, v203, v88, vcc
	v_cmp_le_i32_e32 vcc, v245, v231
	s_nop 1
	v_cndmask_b32_e32 v105, v203, v105, vcc
	v_cmp_le_i32_e32 vcc, v245, v232
	s_nop 1
	v_cndmask_b32_e32 v89, v203, v89, vcc
	v_cmp_le_i32_e32 vcc, v245, v233
	s_nop 1
	v_cndmask_b32_e32 v106, v203, v106, vcc
	v_cmp_le_i32_e32 vcc, v245, v234
	s_nop 1
	v_cndmask_b32_e32 v90, v203, v90, vcc
	v_cmp_le_i32_e32 vcc, v245, v235
	s_nop 1
	v_cndmask_b32_e32 v107, v203, v107, vcc
	v_cmp_le_i32_e32 vcc, v245, v236
	s_nop 1
	v_cndmask_b32_e32 v91, v203, v91, vcc
	v_cmp_le_i32_e32 vcc, v245, v237
	s_nop 1
	v_cndmask_b32_e32 v108, v203, v108, vcc
	v_cmp_le_i32_e32 vcc, v245, v238
	s_nop 1
	v_cndmask_b32_e32 v92, v203, v92, vcc
	v_cmp_le_i32_e32 vcc, v245, v239
	s_nop 1
	v_cndmask_b32_e32 v109, v203, v109, vcc
	v_cmp_le_i32_e32 vcc, v245, v240
	s_nop 1
	v_cndmask_b32_e32 v93, v203, v93, vcc
	v_cmp_le_i32_e32 vcc, v245, v241
	s_nop 1
	v_cndmask_b32_e32 v110, v203, v110, vcc
	v_cmp_le_i32_e32 vcc, v245, v242
	s_nop 1
	v_cndmask_b32_e32 v94, v203, v94, vcc
	v_cmp_le_i32_e32 vcc, v245, v243
	s_nop 1
	v_cndmask_b32_e32 v111, v203, v111, vcc
	v_cmp_le_i32_e32 vcc, v245, v244
	s_nop 1
	v_cndmask_b32_e32 v95, v203, v95, vcc
